# A/B: per-cluster s_setprio flips deleted in the P1 GEMM K-loop
# speedup vs baseline: 1.0028x; 1.0028x over previous
; #define PG8_STAGE(bufoff, gbase, voff) do { _Pragma("unroll") for (int _i = 0; _i < 2; ++_i) \
;         __builtin_amdgcn_global_load_lds((const unsigned*)((const char*)(gbase) + (voff)[_i]), (LAS unsigned*)(lds + (bufoff) + ldsw + _i * 8192), 16, 0, 0); } while (0)
; #define PG8_LDA(dst, b, h) do { _Pragma("unroll") for (int m = 0; m < 4; ++m) _Pragma("unroll") for (int k = 0; k < 2; ++k) dst[m][k] = *(const LAS bf16x8*)(lds + PG8_SA(b, h) + aoff + m * 2048 + k * 1024); } while (0)
; #define PG8_LDB(dst, b, h) do { _Pragma("unroll") for (int n = 0; n < 2; ++n) _Pragma("unroll") for (int k = 0; k < 2; ++k) dst[n][k] = *(const LAS bf16x8*)(lds + PG8_SB(b, h) + boff + n * 2048 + k * 1024); } while (0)
; #define PG8_WAIT_V(n) asm volatile("s_waitcnt vmcnt(" #n ")" ::: "memory")
; #define PG8_WAIT_L(n) asm volatile("s_waitcnt lgkmcnt(" #n ")" ::: "memory")
; #define PG8_BAR __builtin_amdgcn_s_barrier()
; template <class Epi, int AC0, int BC0, int NT0, int AC1, int BC1, int NT1>
; __device__ __forceinline__ void gemm_phase(LAS unsigned char* lds, const Gemm g, const StaticOrder& S, const Epi& E, int tid) {
;     ...
;     Unit cur, nxt; int ui = 0;
;     if (!S.next(0, cur)) return;
;     f32x4 acc[2][2][4][2];
; #pragma unroll
;     for (int a = 0; a < 2; ++a)
; #pragma unroll
;         for (int b = 0; b < 2; ++b)
; #pragma unroll
;             for (int m = 0; m < 4; ++m)
; #pragma unroll
;                 for (int n = 0; n < 2; ++n) acc[a][b][m][n] = (f32x4){0.f, 0.f, 0.f, 0.f};
;     ...
;         for (int t = 0; t < nt; t += 2) {
;             const bool last = (t == nt - 2);
;             const char* a1 = cA + (size_t)(t + 1) * kstep;
;             const char* a2 = last ? nA : cA + (size_t)(t + 2) * kstep; const char* b2 = last ? nB : cB + (size_t)(t + 2) * kstep;
;             const char* a3 = a2 + kstep; const char* b3 = b2 + kstep;
;             PG8_LDB(B0, 0, 0); PG8_LDB(B1, 0, 1); PG8_SCHED; PG8_LDA(At, 0, 0); PG8_STAGE(PG8_SA(1, 1), a1 + hstepA, voffA);
;             PG8_WAIT_V(8); PG8_WAIT_L(0); PG8_BAR; PG8_MMA(0, 0, At, B0); PG8_MMA(0, 1, At, B1); PG8_BAR; PG8_SCHED;
;             PG8_LDA(At, 0, 1); PG8_STAGE(PG8_SB(0, 0), b2, voffB); PG8_STAGE(PG8_SB(0, 1), b2 + hstepB, voffB); PG8_STAGE(PG8_SA(0, 0), a2, voffA);
;             PG8_WAIT_V(8); PG8_WAIT_L(0); PG8_BAR; PG8_MMA(1, 0, At, B0); PG8_MMA(1, 1, At, B1); PG8_BAR; PG8_SCHED;
.Lpeel_P1:
	ds_read_b128 v[26:29], v192
	ds_read_b128 v[30:33], v192 offset:1024
	ds_read_b128 v[42:45], v192 offset:2048
	ds_read_b128 v[46:49], v192 offset:3072
	ds_read_b128 v[146:149], v193
	ds_read_b128 v[150:153], v193 offset:1024
	ds_read_b128 v[154:157], v193 offset:2048
	ds_read_b128 v[158:161], v193 offset:3072
	s_add_u32 s6, s0, 0xfffc0080
	s_addc_u32 s7, s1, -1
	s_cmp_eq_u32 s27, 12
	s_cselect_b32 s13, s3, s7
	s_cselect_b32 s12, s9, s6
	s_cselect_b32 s7, s11, s22
	s_cselect_b32 s6, s15, s16
	v_lshl_add_u64 v[186:187], s[0:1], 0, v[178:179]
	s_add_i32 m0, s95, 0xc000
	ds_read_b128 v[198:201], v194
	ds_read_b128 v[202:205], v194 offset:1024
	ds_read_b128 v[206:209], v194 offset:2048
	ds_read_b128 v[210:213], v194 offset:3072
	ds_read_b128 v[214:217], v194 offset:4096
	ds_read_b128 v[218:221], v194 offset:5120
	ds_read_b128 v[226:229], v194 offset:6144
	ds_read_b128 v[230:233], v194 offset:7168
	global_load_lds_dwordx4 v[186:187], off
	v_lshl_add_u64 v[186:187], s[0:1], 0, v[180:181]
	s_add_i32 m0, s95, 0xe000
	s_nop 0
	global_load_lds_dwordx4 v[186:187], off
	s_waitcnt vmcnt(24)
	s_waitcnt lgkmcnt(0)
	s_barrier
	s_waitcnt lgkmcnt(0)
	v_mfma_f32_16x16x32_bf16 v[142:145], v[26:29], v[198:201], 0
	v_mfma_f32_16x16x32_bf16 v[138:141], v[42:45], v[198:201], 0
	v_mfma_f32_16x16x32_bf16 v[126:129], v[26:29], v[206:209], 0
	v_mfma_f32_16x16x32_bf16 v[122:125], v[42:45], v[206:209], 0
	v_mfma_f32_16x16x32_bf16 v[110:113], v[26:29], v[214:217], 0
	v_mfma_f32_16x16x32_bf16 v[106:109], v[42:45], v[214:217], 0
	v_mfma_f32_16x16x32_bf16 v[94:97], v[26:29], v[226:229], 0
	v_mfma_f32_16x16x32_bf16 v[90:93], v[42:45], v[226:229], 0
	v_mfma_f32_16x16x32_bf16 v[142:145], v[30:33], v[202:205], v[142:145]
	v_mfma_f32_16x16x32_bf16 v[138:141], v[46:49], v[202:205], v[138:141]
	v_mfma_f32_16x16x32_bf16 v[126:129], v[30:33], v[210:213], v[126:129]
	v_mfma_f32_16x16x32_bf16 v[122:125], v[46:49], v[210:213], v[122:125]
	v_mfma_f32_16x16x32_bf16 v[110:113], v[30:33], v[218:221], v[110:113]
	v_mfma_f32_16x16x32_bf16 v[106:109], v[46:49], v[218:221], v[106:109]
	v_mfma_f32_16x16x32_bf16 v[94:97], v[30:33], v[230:233], v[94:97]
	v_mfma_f32_16x16x32_bf16 v[90:93], v[46:49], v[230:233], v[90:93]
	v_mfma_f32_16x16x32_bf16 v[134:137], v[146:149], v[198:201], 0
	v_mfma_f32_16x16x32_bf16 v[130:133], v[154:157], v[198:201], 0
	v_mfma_f32_16x16x32_bf16 v[118:121], v[146:149], v[206:209], 0
	v_mfma_f32_16x16x32_bf16 v[114:117], v[154:157], v[206:209], 0
	v_mfma_f32_16x16x32_bf16 v[102:105], v[146:149], v[214:217], 0
	v_mfma_f32_16x16x32_bf16 v[98:101], v[154:157], v[214:217], 0
	v_mfma_f32_16x16x32_bf16 v[86:89], v[146:149], v[226:229], 0
	v_mfma_f32_16x16x32_bf16 v[82:85], v[154:157], v[226:229], 0
	v_mfma_f32_16x16x32_bf16 v[134:137], v[150:153], v[202:205], v[134:137]
	v_mfma_f32_16x16x32_bf16 v[130:133], v[158:161], v[202:205], v[130:133]
	v_mfma_f32_16x16x32_bf16 v[118:121], v[150:153], v[210:213], v[118:121]
	v_mfma_f32_16x16x32_bf16 v[114:117], v[158:161], v[210:213], v[114:117]
	v_mfma_f32_16x16x32_bf16 v[102:105], v[150:153], v[218:221], v[102:105]
	v_mfma_f32_16x16x32_bf16 v[98:101], v[158:161], v[218:221], v[98:101]
	v_mfma_f32_16x16x32_bf16 v[86:89], v[150:153], v[230:233], v[86:89]
	v_mfma_f32_16x16x32_bf16 v[82:85], v[158:161], v[230:233], v[82:85]
	s_barrier
	s_add_i32 s29, s94, s47
	v_lshl_add_u64 v[186:187], s[6:7], 0, v[166:167]
	s_mov_b32 m0, s29
	ds_read_b128 v[198:201], v194 offset:16384
	ds_read_b128 v[202:205], v194 offset:17408
	ds_read_b128 v[206:209], v194 offset:18432
	ds_read_b128 v[210:213], v194 offset:19456
	ds_read_b128 v[214:217], v194 offset:20480
	ds_read_b128 v[218:221], v194 offset:21504
	ds_read_b128 v[226:229], v194 offset:22528
	ds_read_b128 v[230:233], v194 offset:23552
	global_load_lds_dwordx4 v[186:187], off
	s_add_i32 m0, s29, 0x2000
	s_add_u32 s36, s6, 0x40000
	v_lshl_add_u64 v[222:223], s[6:7], 0, v[170:171]
	s_addc_u32 s37, s7, 0
	s_add_i32 s29, s18, s47
	global_load_lds_dwordx4 v[222:223], off
	v_lshl_add_u64 v[234:235], s[36:37], 0, v[166:167]
	s_mov_b32 m0, s29
	v_lshl_add_u64 v[236:237], s[12:13], 0, v[168:169]
	global_load_lds_dwordx4 v[234:235], off
	v_lshl_add_u64 v[234:235], s[36:37], 0, v[170:171]
	s_add_i32 m0, s29, 0x2000
	s_nop 0
	global_load_lds_dwordx4 v[234:235], off
	v_lshl_add_u64 v[234:235], s[12:13], 0, v[164:165]
	s_mov_b32 m0, s95
	s_nop 0
	global_load_lds_dwordx4 v[234:235], off
	s_mov_b32 m0, s96
	s_nop 0
	global_load_lds_dwordx4 v[236:237], off
	s_waitcnt vmcnt(8)
	s_waitcnt lgkmcnt(0)
	s_barrier
	s_waitcnt lgkmcnt(0)
	v_mfma_f32_16x16x32_bf16 v[78:81], v[26:29], v[198:201], 0
	v_mfma_f32_16x16x32_bf16 v[74:77], v[42:45], v[198:201], 0
	v_mfma_f32_16x16x32_bf16 v[62:65], v[26:29], v[206:209], 0
	v_mfma_f32_16x16x32_bf16 v[58:61], v[42:45], v[206:209], 0
	v_mfma_f32_16x16x32_bf16 v[38:41], v[26:29], v[214:217], 0
	v_mfma_f32_16x16x32_bf16 v[34:37], v[42:45], v[214:217], 0
	v_mfma_f32_16x16x32_bf16 v[14:17], v[26:29], v[226:229], 0
	v_mfma_f32_16x16x32_bf16 v[10:13], v[42:45], v[226:229], 0
	v_mfma_f32_16x16x32_bf16 v[78:81], v[30:33], v[202:205], v[78:81]
	v_mfma_f32_16x16x32_bf16 v[74:77], v[46:49], v[202:205], v[74:77]
	v_mfma_f32_16x16x32_bf16 v[62:65], v[30:33], v[210:213], v[62:65]
	v_mfma_f32_16x16x32_bf16 v[58:61], v[46:49], v[210:213], v[58:61]
	v_mfma_f32_16x16x32_bf16 v[38:41], v[30:33], v[218:221], v[38:41]
	v_mfma_f32_16x16x32_bf16 v[34:37], v[46:49], v[218:221], v[34:37]
	v_mfma_f32_16x16x32_bf16 v[14:17], v[30:33], v[230:233], v[14:17]
	v_mfma_f32_16x16x32_bf16 v[10:13], v[46:49], v[230:233], v[10:13]
	v_mfma_f32_16x16x32_bf16 v[22:25], v[146:149], v[214:217], 0
	v_mfma_f32_16x16x32_bf16 v[18:21], v[154:157], v[214:217], 0
	v_mfma_f32_16x16x32_bf16 v[6:9], v[146:149], v[226:229], 0
	v_mfma_f32_16x16x32_bf16 v[2:5], v[154:157], v[226:229], 0
	v_mfma_f32_16x16x32_bf16 v[26:29], v[146:149], v[198:201], 0
	v_mfma_f32_16x16x32_bf16 v[30:33], v[154:157], v[198:201], 0
	v_mfma_f32_16x16x32_bf16 v[42:45], v[146:149], v[206:209], 0
	v_mfma_f32_16x16x32_bf16 v[46:49], v[154:157], v[206:209], 0
	v_mfma_f32_16x16x32_bf16 v[22:25], v[150:153], v[218:221], v[22:25]
	v_mfma_f32_16x16x32_bf16 v[18:21], v[158:161], v[218:221], v[18:21]
	v_mfma_f32_16x16x32_bf16 v[6:9], v[150:153], v[230:233], v[6:9]
	v_mfma_f32_16x16x32_bf16 v[2:5], v[158:161], v[230:233], v[2:5]
	v_mfma_f32_16x16x32_bf16 v[26:29], v[150:153], v[202:205], v[26:29]
	v_mfma_f32_16x16x32_bf16 v[30:33], v[158:161], v[202:205], v[30:33]
	v_mfma_f32_16x16x32_bf16 v[42:45], v[150:153], v[210:213], v[42:45]
	v_mfma_f32_16x16x32_bf16 v[46:49], v[158:161], v[210:213], v[46:49]
	s_barrier
	s_branch .Lmid_P1

; #define PG8_STAGE(bufoff, gbase, voff) do { _Pragma("unroll") for (int _i = 0; _i < 2; ++_i) \
;         __builtin_amdgcn_global_load_lds((const unsigned*)((const char*)(gbase) + (voff)[_i]), (LAS unsigned*)(lds + (bufoff) + ldsw + _i * 8192), 16, 0, 0); } while (0)
; #define PG8_LDA(dst, b, h) do { _Pragma("unroll") for (int m = 0; m < 4; ++m) _Pragma("unroll") for (int k = 0; k < 2; ++k) dst[m][k] = *(const LAS bf16x8*)(lds + PG8_SA(b, h) + aoff + m * 2048 + k * 1024); } while (0)
; #define PG8_LDB(dst, b, h) do { _Pragma("unroll") for (int n = 0; n < 2; ++n) _Pragma("unroll") for (int k = 0; k < 2; ++k) dst[n][k] = *(const LAS bf16x8*)(lds + PG8_SB(b, h) + boff + n * 2048 + k * 1024); } while (0)
; #define PG8_MMA(ai, bj, At, Bt) do { __builtin_amdgcn_s_setprio(1); _Pragma("unroll") for (int m = 0; m < 4; ++m) _Pragma("unroll") for (int n = 0; n < 2; ++n) _Pragma("unroll") for (int k = 0; k < 2; ++k) \
;         acc[ai][bj][m][n] = __builtin_amdgcn_mfma_f32_16x16x32_bf16(Bt[n][k], At[m][k], acc[ai][bj][m][n], 0, 0, 0); __builtin_amdgcn_s_setprio(0); } while (0)
; #define PG8_WAIT_V(n) asm volatile("s_waitcnt vmcnt(" #n ")" ::: "memory")
; #define PG8_WAIT_L(n) asm volatile("s_waitcnt lgkmcnt(" #n ")" ::: "memory")
; #define PG8_BAR __builtin_amdgcn_s_barrier()
; #define PG8_SCHED __builtin_amdgcn_sched_barrier(0)
; template <class Epi, int AC0, int BC0, int NT0, int AC1, int BC1, int NT1>
; __device__ __forceinline__ void gemm_phase(LAS unsigned char* lds, const Gemm g, const StaticOrder& S, const Epi& E, int tid) {
;     ...
;             const bool last = (t == nt - 2);
;             const char* a1 = cA + (size_t)(t + 1) * kstep;
;             const char* a2 = last ? nA : cA + (size_t)(t + 2) * kstep; const char* b2 = last ? nB : cB + (size_t)(t + 2) * kstep;
;             const char* a3 = a2 + kstep; const char* b3 = b2 + kstep;
;             PG8_LDB(B0, 0, 0); PG8_LDB(B1, 0, 1); PG8_SCHED; PG8_LDA(At, 0, 0); PG8_STAGE(PG8_SA(1, 1), a1 + hstepA, voffA);
;             PG8_WAIT_V(8); PG8_WAIT_L(0); PG8_BAR; PG8_MMA(0, 0, At, B0); PG8_MMA(0, 1, At, B1); PG8_BAR; PG8_SCHED;
;             PG8_LDA(At, 0, 1); PG8_STAGE(PG8_SB(0, 0), b2, voffB); PG8_STAGE(PG8_SB(0, 1), b2 + hstepB, voffB); PG8_STAGE(PG8_SA(0, 0), a2, voffA);
;             PG8_WAIT_V(8); PG8_WAIT_L(0); PG8_BAR; PG8_MMA(1, 0, At, B0); PG8_MMA(1, 1, At, B1); PG8_BAR; PG8_SCHED;
.LBB0_124:
	ds_read_b128 v[26:29], v192
	ds_read_b128 v[30:33], v192 offset:1024
	ds_read_b128 v[42:45], v192 offset:2048
	ds_read_b128 v[46:49], v192 offset:3072
	ds_read_b128 v[146:149], v193
	ds_read_b128 v[150:153], v193 offset:1024
	ds_read_b128 v[154:157], v193 offset:2048
	ds_read_b128 v[158:161], v193 offset:3072
	s_add_u32 s6, s0, 0xfffc0080
	s_addc_u32 s7, s1, -1
	s_cmp_eq_u32 s27, 12
	s_cselect_b32 s13, s3, s7
	s_cselect_b32 s12, s9, s6
	s_cselect_b32 s7, s11, s22
	s_cselect_b32 s6, s15, s16
	v_lshl_add_u64 v[186:187], s[0:1], 0, v[178:179]
	s_add_i32 m0, s95, 0xc000
	ds_read_b128 v[198:201], v194
	ds_read_b128 v[202:205], v194 offset:1024
	ds_read_b128 v[206:209], v194 offset:2048
	ds_read_b128 v[210:213], v194 offset:3072
	ds_read_b128 v[214:217], v194 offset:4096
	ds_read_b128 v[218:221], v194 offset:5120
	ds_read_b128 v[226:229], v194 offset:6144
	ds_read_b128 v[230:233], v194 offset:7168
	global_load_lds_dwordx4 v[186:187], off
	v_lshl_add_u64 v[186:187], s[0:1], 0, v[180:181]
	s_add_i32 m0, s95, 0xe000
	s_nop 0
	global_load_lds_dwordx4 v[186:187], off
	s_waitcnt vmcnt(8)
	s_waitcnt lgkmcnt(0)
	s_barrier
	s_waitcnt lgkmcnt(0)
	v_mfma_f32_16x16x32_bf16 v[142:145], v[26:29], v[198:201], v[142:145]
	v_mfma_f32_16x16x32_bf16 v[138:141], v[42:45], v[198:201], v[138:141]
	v_mfma_f32_16x16x32_bf16 v[126:129], v[26:29], v[206:209], v[126:129]
	v_mfma_f32_16x16x32_bf16 v[122:125], v[42:45], v[206:209], v[122:125]
	v_mfma_f32_16x16x32_bf16 v[110:113], v[26:29], v[214:217], v[110:113]
	v_mfma_f32_16x16x32_bf16 v[106:109], v[42:45], v[214:217], v[106:109]
	v_mfma_f32_16x16x32_bf16 v[94:97], v[26:29], v[226:229], v[94:97]
	v_mfma_f32_16x16x32_bf16 v[90:93], v[42:45], v[226:229], v[90:93]
	v_mfma_f32_16x16x32_bf16 v[142:145], v[30:33], v[202:205], v[142:145]
	v_mfma_f32_16x16x32_bf16 v[138:141], v[46:49], v[202:205], v[138:141]
	v_mfma_f32_16x16x32_bf16 v[126:129], v[30:33], v[210:213], v[126:129]
	v_mfma_f32_16x16x32_bf16 v[122:125], v[46:49], v[210:213], v[122:125]
	v_mfma_f32_16x16x32_bf16 v[110:113], v[30:33], v[218:221], v[110:113]
	v_mfma_f32_16x16x32_bf16 v[106:109], v[46:49], v[218:221], v[106:109]
	v_mfma_f32_16x16x32_bf16 v[94:97], v[30:33], v[230:233], v[94:97]
	v_mfma_f32_16x16x32_bf16 v[90:93], v[46:49], v[230:233], v[90:93]
	v_mfma_f32_16x16x32_bf16 v[134:137], v[146:149], v[198:201], v[134:137]
	v_mfma_f32_16x16x32_bf16 v[130:133], v[154:157], v[198:201], v[130:133]
	v_mfma_f32_16x16x32_bf16 v[118:121], v[146:149], v[206:209], v[118:121]
	v_mfma_f32_16x16x32_bf16 v[114:117], v[154:157], v[206:209], v[114:117]
	v_mfma_f32_16x16x32_bf16 v[102:105], v[146:149], v[214:217], v[102:105]
	v_mfma_f32_16x16x32_bf16 v[98:101], v[154:157], v[214:217], v[98:101]
	v_mfma_f32_16x16x32_bf16 v[86:89], v[146:149], v[226:229], v[86:89]
	v_mfma_f32_16x16x32_bf16 v[82:85], v[154:157], v[226:229], v[82:85]
	v_mfma_f32_16x16x32_bf16 v[134:137], v[150:153], v[202:205], v[134:137]
	v_mfma_f32_16x16x32_bf16 v[130:133], v[158:161], v[202:205], v[130:133]
	v_mfma_f32_16x16x32_bf16 v[118:121], v[150:153], v[210:213], v[118:121]
	v_mfma_f32_16x16x32_bf16 v[114:117], v[158:161], v[210:213], v[114:117]
	v_mfma_f32_16x16x32_bf16 v[102:105], v[150:153], v[218:221], v[102:105]
	v_mfma_f32_16x16x32_bf16 v[98:101], v[158:161], v[218:221], v[98:101]
	v_mfma_f32_16x16x32_bf16 v[86:89], v[150:153], v[230:233], v[86:89]
	v_mfma_f32_16x16x32_bf16 v[82:85], v[158:161], v[230:233], v[82:85]
	s_barrier
	s_add_i32 s29, s94, s47
	v_lshl_add_u64 v[186:187], s[6:7], 0, v[166:167]
	s_mov_b32 m0, s29
	ds_read_b128 v[198:201], v194 offset:16384
	ds_read_b128 v[202:205], v194 offset:17408
	ds_read_b128 v[206:209], v194 offset:18432
	ds_read_b128 v[210:213], v194 offset:19456
	ds_read_b128 v[214:217], v194 offset:20480
	ds_read_b128 v[218:221], v194 offset:21504
	ds_read_b128 v[226:229], v194 offset:22528
	ds_read_b128 v[230:233], v194 offset:23552
	global_load_lds_dwordx4 v[186:187], off
	s_add_i32 m0, s29, 0x2000
	s_add_u32 s36, s6, 0x40000
	v_lshl_add_u64 v[222:223], s[6:7], 0, v[170:171]
	s_addc_u32 s37, s7, 0
	s_add_i32 s29, s18, s47
	global_load_lds_dwordx4 v[222:223], off
	v_lshl_add_u64 v[234:235], s[36:37], 0, v[166:167]
	s_mov_b32 m0, s29
	v_lshl_add_u64 v[236:237], s[12:13], 0, v[168:169]
	global_load_lds_dwordx4 v[234:235], off
	v_lshl_add_u64 v[234:235], s[36:37], 0, v[170:171]
	s_add_i32 m0, s29, 0x2000
	s_nop 0
	global_load_lds_dwordx4 v[234:235], off
	v_lshl_add_u64 v[234:235], s[12:13], 0, v[164:165]
	s_mov_b32 m0, s95
	s_nop 0
	global_load_lds_dwordx4 v[234:235], off
	s_mov_b32 m0, s96
	s_nop 0
	global_load_lds_dwordx4 v[236:237], off
	s_waitcnt vmcnt(8)
	s_waitcnt lgkmcnt(0)
	s_barrier
	s_waitcnt lgkmcnt(0)
	v_mfma_f32_16x16x32_bf16 v[78:81], v[26:29], v[198:201], v[78:81]
	v_mfma_f32_16x16x32_bf16 v[74:77], v[42:45], v[198:201], v[74:77]
	v_mfma_f32_16x16x32_bf16 v[62:65], v[26:29], v[206:209], v[62:65]
	v_mfma_f32_16x16x32_bf16 v[58:61], v[42:45], v[206:209], v[58:61]
	v_mfma_f32_16x16x32_bf16 v[38:41], v[26:29], v[214:217], v[38:41]
	v_mfma_f32_16x16x32_bf16 v[34:37], v[42:45], v[214:217], v[34:37]
	v_mfma_f32_16x16x32_bf16 v[14:17], v[26:29], v[226:229], v[14:17]
	v_mfma_f32_16x16x32_bf16 v[10:13], v[42:45], v[226:229], v[10:13]
	v_mfma_f32_16x16x32_bf16 v[78:81], v[30:33], v[202:205], v[78:81]
	v_mfma_f32_16x16x32_bf16 v[74:77], v[46:49], v[202:205], v[74:77]
	v_mfma_f32_16x16x32_bf16 v[62:65], v[30:33], v[210:213], v[62:65]
	v_mfma_f32_16x16x32_bf16 v[58:61], v[46:49], v[210:213], v[58:61]
	v_mfma_f32_16x16x32_bf16 v[38:41], v[30:33], v[218:221], v[38:41]
	v_mfma_f32_16x16x32_bf16 v[34:37], v[46:49], v[218:221], v[34:37]
	v_mfma_f32_16x16x32_bf16 v[14:17], v[30:33], v[230:233], v[14:17]
	v_mfma_f32_16x16x32_bf16 v[10:13], v[46:49], v[230:233], v[10:13]
	v_mfma_f32_16x16x32_bf16 v[22:25], v[146:149], v[214:217], v[22:25]
	v_mfma_f32_16x16x32_bf16 v[18:21], v[154:157], v[214:217], v[18:21]
	v_mfma_f32_16x16x32_bf16 v[6:9], v[146:149], v[226:229], v[6:9]
	v_mfma_f32_16x16x32_bf16 v[2:5], v[154:157], v[226:229], v[2:5]
	v_mfma_f32_16x16x32_bf16 v[26:29], v[146:149], v[198:201], v[70:73]
	v_mfma_f32_16x16x32_bf16 v[30:33], v[154:157], v[198:201], v[66:69]
	v_mfma_f32_16x16x32_bf16 v[42:45], v[146:149], v[206:209], v[54:57]
	v_mfma_f32_16x16x32_bf16 v[46:49], v[154:157], v[206:209], v[50:53]
	v_mfma_f32_16x16x32_bf16 v[22:25], v[150:153], v[218:221], v[22:25]
	v_mfma_f32_16x16x32_bf16 v[18:21], v[158:161], v[218:221], v[18:21]
	v_mfma_f32_16x16x32_bf16 v[6:9], v[150:153], v[230:233], v[6:9]
	v_mfma_f32_16x16x32_bf16 v[2:5], v[158:161], v[230:233], v[2:5]
	v_mfma_f32_16x16x32_bf16 v[26:29], v[150:153], v[202:205], v[26:29]
	v_mfma_f32_16x16x32_bf16 v[30:33], v[158:161], v[202:205], v[30:33]
	v_mfma_f32_16x16x32_bf16 v[42:45], v[150:153], v[210:213], v[42:45]
	v_mfma_f32_16x16x32_bf16 v[46:49], v[158:161], v[210:213], v[46:49]
	s_barrier
; #define PG8_STAGE(bufoff, gbase, voff) do { _Pragma("unroll") for (int _i = 0; _i < 2; ++_i) \
;         __builtin_amdgcn_global_load_lds((const unsigned*)((const char*)(gbase) + (voff)[_i]), (LAS unsigned*)(lds + (bufoff) + ldsw + _i * 8192), 16, 0, 0); } while (0)
; #define PG8_LDA(dst, b, h) do { _Pragma("unroll") for (int m = 0; m < 4; ++m) _Pragma("unroll") for (int k = 0; k < 2; ++k) dst[m][k] = *(const LAS bf16x8*)(lds + PG8_SA(b, h) + aoff + m * 2048 + k * 1024); } while (0)
; #define PG8_LDB(dst, b, h) do { _Pragma("unroll") for (int n = 0; n < 2; ++n) _Pragma("unroll") for (int k = 0; k < 2; ++k) dst[n][k] = *(const LAS bf16x8*)(lds + PG8_SB(b, h) + boff + n * 2048 + k * 1024); } while (0)
; #define PG8_MMA(ai, bj, At, Bt) do { __builtin_amdgcn_s_setprio(1); _Pragma("unroll") for (int m = 0; m < 4; ++m) _Pragma("unroll") for (int n = 0; n < 2; ++n) _Pragma("unroll") for (int k = 0; k < 2; ++k) \
;         acc[ai][bj][m][n] = __builtin_amdgcn_mfma_f32_16x16x32_bf16(Bt[n][k], At[m][k], acc[ai][bj][m][n], 0, 0, 0); __builtin_amdgcn_s_setprio(0); } while (0)
; #define PG8_WAIT_V(n) asm volatile("s_waitcnt vmcnt(" #n ")" ::: "memory")
; #define PG8_WAIT_L(n) asm volatile("s_waitcnt lgkmcnt(" #n ")" ::: "memory")
; #define PG8_BAR __builtin_amdgcn_s_barrier()
; #define PG8_SCHED __builtin_amdgcn_sched_barrier(0)
; template <class Epi, int AC0, int BC0, int NT0, int AC1, int BC1, int NT1>
; __device__ __forceinline__ void gemm_phase(LAS unsigned char* lds, const Gemm g, const StaticOrder& S, const Epi& E, int tid) {
;     ...
;             PG8_LDB(B0, 1, 0); PG8_LDB(B1, 1, 1); PG8_SCHED; PG8_LDA(At, 1, 0); PG8_STAGE(PG8_SA(0, 1), a2 + hstepA, voffA);
;             PG8_WAIT_V(8); PG8_WAIT_L(0); PG8_BAR; PG8_MMA(0, 0, At, B0); PG8_MMA(0, 1, At, B1); PG8_BAR; PG8_SCHED;
.Lmid_P1:
	s_add_i32 s29, 0, 0x18000
	s_add_i32 s33, 0, 0x1c000
	v_add_u32_e32 v70, s29, v188
	v_add_u32_e32 v158, s33, v188
	ds_read_b128 v[50:53], v70
	ds_read_b128 v[54:57], v70 offset:1024
	ds_read_b128 v[66:69], v70 offset:2048
	ds_read_b128 v[70:73], v70 offset:3072
	ds_read_b128 v[146:149], v158
	ds_read_b128 v[150:153], v158 offset:1024
	ds_read_b128 v[154:157], v158 offset:2048
	ds_read_b128 v[158:161], v158 offset:3072
	s_add_u32 s12, s12, 0x40000
	s_addc_u32 s13, s13, 0
	s_mov_b32 m0, s97
	v_lshl_add_u64 v[238:239], s[12:13], 0, v[164:165]
	ds_read_b128 v[198:201], v194 offset:32768
	ds_read_b128 v[202:205], v194 offset:33792
	ds_read_b128 v[206:209], v194 offset:34816
	ds_read_b128 v[210:213], v194 offset:35840
	ds_read_b128 v[214:217], v194 offset:36864
	ds_read_b128 v[218:221], v194 offset:37888
	ds_read_b128 v[226:229], v194 offset:38912
	ds_read_b128 v[230:233], v194 offset:39936
	global_load_lds_dwordx4 v[238:239], off
	v_lshl_add_u64 v[238:239], s[12:13], 0, v[168:169]
	s_mov_b32 m0, s93
	s_nop 0
	global_load_lds_dwordx4 v[238:239], off
	s_waitcnt vmcnt(8)
	s_waitcnt lgkmcnt(0)
	s_barrier
	s_waitcnt lgkmcnt(0)
	v_mfma_f32_16x16x32_bf16 v[142:145], v[50:53], v[198:201], v[142:145]
	v_mfma_f32_16x16x32_bf16 v[138:141], v[66:69], v[198:201], v[138:141]
	v_mfma_f32_16x16x32_bf16 v[126:129], v[50:53], v[206:209], v[126:129]
	v_mfma_f32_16x16x32_bf16 v[122:125], v[66:69], v[206:209], v[122:125]
	v_mfma_f32_16x16x32_bf16 v[110:113], v[50:53], v[214:217], v[110:113]
	v_mfma_f32_16x16x32_bf16 v[106:109], v[66:69], v[214:217], v[106:109]
	v_mfma_f32_16x16x32_bf16 v[94:97], v[50:53], v[226:229], v[94:97]
	v_mfma_f32_16x16x32_bf16 v[90:93], v[66:69], v[226:229], v[90:93]
	v_mfma_f32_16x16x32_bf16 v[142:145], v[54:57], v[202:205], v[142:145]
	v_mfma_f32_16x16x32_bf16 v[138:141], v[70:73], v[202:205], v[138:141]
	v_mfma_f32_16x16x32_bf16 v[126:129], v[54:57], v[210:213], v[126:129]
	v_mfma_f32_16x16x32_bf16 v[122:125], v[70:73], v[210:213], v[122:125]
	v_mfma_f32_16x16x32_bf16 v[110:113], v[54:57], v[218:221], v[110:113]
	v_mfma_f32_16x16x32_bf16 v[106:109], v[70:73], v[218:221], v[106:109]
	v_mfma_f32_16x16x32_bf16 v[94:97], v[54:57], v[230:233], v[94:97]
	v_mfma_f32_16x16x32_bf16 v[90:93], v[70:73], v[230:233], v[90:93]
	v_mfma_f32_16x16x32_bf16 v[134:137], v[146:149], v[198:201], v[134:137]
	v_mfma_f32_16x16x32_bf16 v[130:133], v[154:157], v[198:201], v[130:133]
	v_mfma_f32_16x16x32_bf16 v[118:121], v[146:149], v[206:209], v[118:121]
	v_mfma_f32_16x16x32_bf16 v[114:117], v[154:157], v[206:209], v[114:117]
	v_mfma_f32_16x16x32_bf16 v[102:105], v[146:149], v[214:217], v[102:105]
	v_mfma_f32_16x16x32_bf16 v[98:101], v[154:157], v[214:217], v[98:101]
	v_mfma_f32_16x16x32_bf16 v[86:89], v[146:149], v[226:229], v[86:89]
	v_mfma_f32_16x16x32_bf16 v[82:85], v[154:157], v[226:229], v[82:85]
	v_mfma_f32_16x16x32_bf16 v[134:137], v[150:153], v[202:205], v[134:137]
	v_mfma_f32_16x16x32_bf16 v[130:133], v[158:161], v[202:205], v[130:133]
	v_mfma_f32_16x16x32_bf16 v[118:121], v[150:153], v[210:213], v[118:121]
	v_mfma_f32_16x16x32_bf16 v[114:117], v[158:161], v[210:213], v[114:117]
	v_mfma_f32_16x16x32_bf16 v[102:105], v[150:153], v[218:221], v[102:105]
	v_mfma_f32_16x16x32_bf16 v[98:101], v[158:161], v[218:221], v[98:101]
	v_mfma_f32_16x16x32_bf16 v[86:89], v[150:153], v[230:233], v[86:89]
	v_mfma_f32_16x16x32_bf16 v[82:85], v[158:161], v[230:233], v[82:85]
	s_barrier
; #define PG8_STAGE(bufoff, gbase, voff) do { _Pragma("unroll") for (int _i = 0; _i < 2; ++_i) \
;         __builtin_amdgcn_global_load_lds((const unsigned*)((const char*)(gbase) + (voff)[_i]), (LAS unsigned*)(lds + (bufoff) + ldsw + _i * 8192), 16, 0, 0); } while (0)
; #define PG8_LDA(dst, b, h) do { _Pragma("unroll") for (int m = 0; m < 4; ++m) _Pragma("unroll") for (int k = 0; k < 2; ++k) dst[m][k] = *(const LAS bf16x8*)(lds + PG8_SA(b, h) + aoff + m * 2048 + k * 1024); } while (0)
; #define PG8_MMA(ai, bj, At, Bt) do { __builtin_amdgcn_s_setprio(1); _Pragma("unroll") for (int m = 0; m < 4; ++m) _Pragma("unroll") for (int n = 0; n < 2; ++n) _Pragma("unroll") for (int k = 0; k < 2; ++k) \
;         acc[ai][bj][m][n] = __builtin_amdgcn_mfma_f32_16x16x32_bf16(Bt[n][k], At[m][k], acc[ai][bj][m][n], 0, 0, 0); __builtin_amdgcn_s_setprio(0); } while (0)
; #define PG8_WAIT_V(n) asm volatile("s_waitcnt vmcnt(" #n ")" ::: "memory")
; #define PG8_WAIT_L(n) asm volatile("s_waitcnt lgkmcnt(" #n ")" ::: "memory")
; #define PG8_BAR __builtin_amdgcn_s_barrier()
; #define PG8_SCHED __builtin_amdgcn_sched_barrier(0)
; template <class Epi, int AC0, int BC0, int NT0, int AC1, int BC1, int NT1>
; __device__ __forceinline__ void gemm_phase(LAS unsigned char* lds, const Gemm g, const StaticOrder& S, const Epi& E, int tid) {
;     ...
;             PG8_LDA(At, 1, 1); PG8_STAGE(PG8_SB(1, 0), b3, voffB); PG8_STAGE(PG8_SB(1, 1), b3 + hstepB, voffB); PG8_STAGE(PG8_SA(1, 0), a3, voffA);
;             PG8_WAIT_V(8); PG8_WAIT_L(0); PG8_BAR; PG8_MMA(1, 0, At, B0); PG8_MMA(1, 1, At, B1); PG8_BAR; PG8_SCHED;
;         }
	s_add_i32 s12, s29, s47
	v_lshl_add_u64 v[186:187], v[186:187], 0, s[20:21]
	s_mov_b32 m0, s12
	ds_read_b128 v[198:201], v194 offset:49152
	ds_read_b128 v[202:205], v194 offset:50176
	ds_read_b128 v[206:209], v194 offset:51200
	ds_read_b128 v[210:213], v194 offset:52224
	ds_read_b128 v[214:217], v194 offset:53248
	ds_read_b128 v[218:221], v194 offset:54272
	ds_read_b128 v[226:229], v194 offset:55296
	ds_read_b128 v[230:233], v194 offset:56320
	global_load_lds_dwordx4 v[186:187], off
	s_add_i32 m0, s12, 0x2000
	s_add_u32 s6, s6, 0x40080
	v_lshl_add_u64 v[186:187], v[222:223], 0, s[20:21]
	s_addc_u32 s7, s7, 0
	s_add_i32 s12, s33, s47
	global_load_lds_dwordx4 v[186:187], off
	v_lshl_add_u64 v[186:187], s[6:7], 0, v[166:167]
	s_mov_b32 m0, s12
	s_nop 0
	global_load_lds_dwordx4 v[186:187], off
	v_lshl_add_u64 v[186:187], s[6:7], 0, v[170:171]
	s_add_i32 m0, s12, 0x2000
	s_nop 0
	global_load_lds_dwordx4 v[186:187], off
	v_lshl_add_u64 v[186:187], v[234:235], 0, s[20:21]
	s_mov_b32 m0, s19
	s_nop 0
	global_load_lds_dwordx4 v[186:187], off
	v_lshl_add_u64 v[186:187], v[236:237], 0, s[20:21]
	s_mov_b32 m0, s46
	s_nop 0
	global_load_lds_dwordx4 v[186:187], off
	s_waitcnt vmcnt(8)
	s_waitcnt lgkmcnt(0)
	s_barrier
	s_waitcnt lgkmcnt(0)
	v_mfma_f32_16x16x32_bf16 v[78:81], v[50:53], v[198:201], v[78:81]
	v_mfma_f32_16x16x32_bf16 v[74:77], v[66:69], v[198:201], v[74:77]
	v_mfma_f32_16x16x32_bf16 v[62:65], v[50:53], v[206:209], v[62:65]
	v_mfma_f32_16x16x32_bf16 v[58:61], v[66:69], v[206:209], v[58:61]
	v_mfma_f32_16x16x32_bf16 v[38:41], v[50:53], v[214:217], v[38:41]
	v_mfma_f32_16x16x32_bf16 v[34:37], v[66:69], v[214:217], v[34:37]
	v_mfma_f32_16x16x32_bf16 v[14:17], v[50:53], v[226:229], v[14:17]
	v_mfma_f32_16x16x32_bf16 v[10:13], v[66:69], v[226:229], v[10:13]
	v_mfma_f32_16x16x32_bf16 v[78:81], v[54:57], v[202:205], v[78:81]
	v_mfma_f32_16x16x32_bf16 v[74:77], v[70:73], v[202:205], v[74:77]
	v_mfma_f32_16x16x32_bf16 v[62:65], v[54:57], v[210:213], v[62:65]
	v_mfma_f32_16x16x32_bf16 v[58:61], v[70:73], v[210:213], v[58:61]
	v_mfma_f32_16x16x32_bf16 v[38:41], v[54:57], v[218:221], v[38:41]
	v_mfma_f32_16x16x32_bf16 v[34:37], v[70:73], v[218:221], v[34:37]
	v_mfma_f32_16x16x32_bf16 v[14:17], v[54:57], v[230:233], v[14:17]
	v_mfma_f32_16x16x32_bf16 v[10:13], v[70:73], v[230:233], v[10:13]
	v_mfma_f32_16x16x32_bf16 v[26:29], v[146:149], v[198:201], v[26:29]
	v_mfma_f32_16x16x32_bf16 v[70:73], v[150:153], v[202:205], v[26:29]
	v_mfma_f32_16x16x32_bf16 v[26:29], v[154:157], v[198:201], v[30:33]
	v_mfma_f32_16x16x32_bf16 v[66:69], v[158:161], v[202:205], v[26:29]
	v_mfma_f32_16x16x32_bf16 v[26:29], v[146:149], v[206:209], v[42:45]
	v_mfma_f32_16x16x32_bf16 v[54:57], v[150:153], v[210:213], v[26:29]
	v_mfma_f32_16x16x32_bf16 v[26:29], v[154:157], v[206:209], v[46:49]
	v_mfma_f32_16x16x32_bf16 v[22:25], v[146:149], v[214:217], v[22:25]
	v_mfma_f32_16x16x32_bf16 v[18:21], v[154:157], v[214:217], v[18:21]
	v_mfma_f32_16x16x32_bf16 v[6:9], v[146:149], v[226:229], v[6:9]
	v_mfma_f32_16x16x32_bf16 v[2:5], v[154:157], v[226:229], v[2:5]
	v_mfma_f32_16x16x32_bf16 v[50:53], v[158:161], v[210:213], v[26:29]
	v_mfma_f32_16x16x32_bf16 v[22:25], v[150:153], v[218:221], v[22:25]
	v_mfma_f32_16x16x32_bf16 v[18:21], v[158:161], v[218:221], v[18:21]
	v_mfma_f32_16x16x32_bf16 v[6:9], v[150:153], v[230:233], v[6:9]
	v_mfma_f32_16x16x32_bf16 v[2:5], v[158:161], v[230:233], v[2:5]
	s_barrier
	s_add_i32 s27, s27, 2
	s_add_u32 s0, s0, 0x100
	s_addc_u32 s1, s1, 0
	s_add_u32 s16, s16, 0x100
	s_addc_u32 s22, s22, 0
	s_cmp_gt_u32 s27, 13
	s_cbranch_scc0 .LBB0_124
	v_readlane_b32 s0, v254, 21
	v_readlane_b32 s1, v254, 22
	s_and_b64 vcc, exec, s[0:1]
	s_cbranch_vccz .LBB0_127
	s_barrier
